# last FFN-down epilogue (fused final RMSNorm) moved to the LDS-transposed coalesced layout; sample out-proj epilogue in the scan phase likewise
# speedup vs baseline: 1.0554x; 1.0034x over previous
; __device__ __forceinline__ unsigned pk(float lo, float hi) { return pg8::cvt_pk_bf16(lo, hi); }
; __device__ __forceinline__ float dot4(f32x4 v) { return (v[0] * v[0] + v[1] * v[1]) + (v[2] * v[2] + v[3] * v[3]); }
;     __device__ __forceinline__ void operator()(const pg8::f32x4 (&acc)[2][2][4][2], const pg8::Unit& u, int wr, int wc, int fr, int fq) const {
;         const int row0 = u.pm * 256 + wr * 64 + fr;
; #pragma unroll
;         for (int ai = 0; ai < 2; ++ai)
; #pragma unroll
;             for (int m = 0; m < 4; ++m) {
;                 const int row = row0 + ai * 128 + m * 16;
;                 const float* xi = (row < MP) ? xin_p + (size_t)row * DM : xin_s + (size_t)(row - MP) * DM;
;                 float sq = 0.f;
; #pragma unroll
;                 for (int bj = 0; bj < 2; ++bj) { const int col = u.pn * 256 + bj * 128 + wc * 32 + 8 * fq;
;                     const f32x4 a0 = *(const f32x4*)(xi + col) + acc[ai][bj][m][0], a1 = *(const f32x4*)(xi + col + 4) + acc[ai][bj][m][1];
;                     *(f32x4*)(xout + (size_t)row * DM + col) = a0; *(f32x4*)(xout + (size_t)row * DM + col + 4) = a1;
;                     u32x4 w; w.x = pk(a0[0], a0[1]); w.y = pk(a0[2], a0[3]); w.z = pk(a1[0], a1[1]); w.w = pk(a1[2], a1[3]);
;                     *(u32x4*)(xb + (size_t)row * DM + col) = w;
;                     sq += dot4(a0) + dot4(a1); }
;                 sq += __shfl_xor(sq, 16); sq += __shfl_xor(sq, 32);
;                 if (fq == 0) atomicAdd(ssout + row, sq);
;             }
.LBB0_2089:
	s_cmp_lt_u32 s58, 64
	s_cselect_b32 s98, s16, s8
	s_cselect_b32 s99, s17, s9
	s_cselect_b32 s100, 0, 0x4000
	v_mov_b32_e32 v233, s58
	v_lshlrev_b32_e32 v233, 8, v233
	v_add_u32_e32 v233, 0x100000, v233
	v_and_b32_e32 v231, 63, v0
	v_lshrrev_b32_e32 v232, 3, v231
	v_and_b32_e32 v229, 7, v231
	v_and_b32_e32 v158, -16, v163
	v_add_u32_e32 v158, v158, v232
	v_lshl_add_u32 v158, s58, 8, v158
	v_and_b32_e32 v240, -32, v164
	v_lshl_add_u32 v240, v229, 2, v240
	v_lshl_or_b32 v240, s57, 8, v240
	v_lshlrev_b32_e32 v241, 2, v158
	v_lshlrev_b32_e32 v240, 2, v240
	v_lshl_add_u32 v242, v158, 12, v240
	v_subrev_u32_e32 v227, s100, v158
	v_lshl_add_u32 v245, v227, 12, v240
	v_lshrrev_b32_e32 v227, 6, v0
	v_mul_u32_u24_e32 v227, 0x900, v227
	v_add_u32_e32 v227, 0x21000, v227
	v_mul_u32_u24_e32 v230, 0x90, v232
	v_lshl_add_u32 v230, v229, 4, v230
	v_add_u32_e32 v224, v227, v230
	v_and_b32_e32 v230, 15, v231
	v_mul_u32_u24_e32 v230, 0x90, v230
	v_lshrrev_b32_e32 v228, 4, v231
	v_lshl_add_u32 v230, v228, 5, v230
	v_add_u32_e32 v246, v227, v230
	v_add_u32_e32 v226, 0x8000, v245
	global_load_dwordx4 v[176:179], v245, s[98:99]
	global_load_dwordx4 v[180:183], v226, s[98:99]
	global_load_dwordx4 v[184:187], v245, s[98:99] offset:512
	global_load_dwordx4 v[188:191], v226, s[98:99] offset:512
	v_add_u32_e32 v225, 0x10000, v245
	v_add_u32_e32 v226, 0x8000, v225
	global_load_dwordx4 v[192:195], v225, s[98:99]
	global_load_dwordx4 v[196:199], v226, s[98:99]
	global_load_dwordx4 v[200:203], v225, s[98:99] offset:512
	global_load_dwordx4 v[204:207], v226, s[98:99] offset:512
	v_add_u32_e32 v225, 0x20000, v245
	v_add_u32_e32 v226, 0x8000, v225
	global_load_dwordx4 v[208:211], v225, s[98:99]
	global_load_dwordx4 v[212:215], v226, s[98:99]
	global_load_dwordx4 v[216:219], v225, s[98:99] offset:512
	global_load_dwordx4 v[220:223], v226, s[98:99] offset:512
	s_waitcnt vmcnt(8)
	ds_write_b128 v246, v[126:129]
	ds_write_b128 v246, v[122:125] offset:16
	ds_read_b128 v[126:129], v224
	ds_read_b128 v[122:125], v224 offset:1152
	s_waitcnt lgkmcnt(0)
	v_pk_add_f32 v[126:127], v[126:127], v[176:177]
	v_pk_add_f32 v[128:129], v[128:129], v[178:179]
	v_pk_add_f32 v[122:123], v[122:123], v[180:181]
	v_pk_add_f32 v[124:125], v[124:125], v[182:183]
	v_mul_f32_e32 v229, v126, v126
	v_mul_f32_e32 v230, v122, v122
	v_fmac_f32_e32 v229, v127, v127
	v_fmac_f32_e32 v230, v123, v123
	v_fmac_f32_e32 v229, v128, v128
	v_fmac_f32_e32 v230, v124, v124
	v_fmac_f32_e32 v229, v129, v129
	v_fmac_f32_e32 v230, v125, v125
	ds_write_b128 v246, v[118:121]
	ds_write_b128 v246, v[114:117] offset:16
	ds_read_b128 v[118:121], v224
	ds_read_b128 v[114:117], v224 offset:1152
	s_waitcnt lgkmcnt(0)
	v_pk_add_f32 v[118:119], v[118:119], v[184:185]
	v_pk_add_f32 v[120:121], v[120:121], v[186:187]
	v_pk_add_f32 v[114:115], v[114:115], v[188:189]
	v_pk_add_f32 v[116:117], v[116:117], v[190:191]
	v_fmac_f32_e32 v229, v118, v118
	v_fmac_f32_e32 v230, v114, v114
	v_fmac_f32_e32 v229, v119, v119
	v_fmac_f32_e32 v230, v115, v115
	v_fmac_f32_e32 v229, v120, v120
	v_fmac_f32_e32 v230, v116, v116
	v_fmac_f32_e32 v229, v121, v121
	v_fmac_f32_e32 v230, v117, v117
	s_nop 1
	v_add_f32_dpp v229, v229, v229 quad_perm:[1,0,3,2] row_mask:0xf bank_mask:0xf
	v_add_f32_dpp v230, v230, v230 quad_perm:[1,0,3,2] row_mask:0xf bank_mask:0xf
	s_nop 0
	v_add_f32_dpp v229, v229, v229 quad_perm:[2,3,0,1] row_mask:0xf bank_mask:0xf
	v_add_f32_dpp v230, v230, v230 quad_perm:[2,3,0,1] row_mask:0xf bank_mask:0xf
	s_nop 0
	v_add_f32_dpp v229, v229, v229 row_half_mirror row_mask:0xf bank_mask:0xf
	v_add_f32_dpp v230, v230, v230 row_half_mirror row_mask:0xf bank_mask:0xf
	s_nop 0
	s_mov_b32 exec_lo, 0x1010101
	s_mov_b32 exec_hi, 0x1010101
	global_atomic_add_f32 v241, v229, s[10:11]
	global_atomic_add_f32 v241, v230, s[10:11] offset:32
	s_mov_b64 exec, -1
	v_add_u32_e32 v225, 0x30000, v245
	v_add_u32_e32 v226, 0x8000, v225
	global_load_dwordx4 v[176:179], v225, s[98:99]
	global_load_dwordx4 v[180:183], v226, s[98:99]
	global_load_dwordx4 v[184:187], v225, s[98:99] offset:512
	global_load_dwordx4 v[188:191], v226, s[98:99] offset:512
	s_waitcnt vmcnt(10)
	ds_write_b128 v246, v[110:113]
	ds_write_b128 v246, v[106:109] offset:16
	ds_read_b128 v[110:113], v224
	ds_read_b128 v[106:109], v224 offset:1152
	s_waitcnt lgkmcnt(0)
	v_pk_add_f32 v[110:111], v[110:111], v[192:193]
	v_pk_add_f32 v[112:113], v[112:113], v[194:195]
	v_pk_add_f32 v[106:107], v[106:107], v[196:197]
	v_pk_add_f32 v[108:109], v[108:109], v[198:199]
	v_mul_f32_e32 v229, v110, v110
	v_mul_f32_e32 v230, v106, v106
	v_fmac_f32_e32 v229, v111, v111
	v_fmac_f32_e32 v230, v107, v107
	v_fmac_f32_e32 v229, v112, v112
	v_fmac_f32_e32 v230, v108, v108
	v_fmac_f32_e32 v229, v113, v113
	v_fmac_f32_e32 v230, v109, v109
	ds_write_b128 v246, v[102:105]
	ds_write_b128 v246, v[98:101] offset:16
	ds_read_b128 v[102:105], v224
	ds_read_b128 v[98:101], v224 offset:1152
	s_waitcnt lgkmcnt(0)
; __device__ __forceinline__ unsigned pk(float lo, float hi) { return pg8::cvt_pk_bf16(lo, hi); }
; __device__ __forceinline__ float dot4(f32x4 v) { return (v[0] * v[0] + v[1] * v[1]) + (v[2] * v[2] + v[3] * v[3]); }
;     __device__ __forceinline__ void operator()(const pg8::f32x4 (&acc)[2][2][4][2], const pg8::Unit& u, int wr, int wc, int fr, int fq) const {
;     ...
;             for (int m = 0; m < 4; ++m) {
;                 const int row = row0 + ai * 128 + m * 16;
;                 const float* xi = (row < MP) ? xin_p + (size_t)row * DM : xin_s + (size_t)(row - MP) * DM;
;                 float sq = 0.f;
; #pragma unroll
;                 for (int bj = 0; bj < 2; ++bj) { const int col = u.pn * 256 + bj * 128 + wc * 32 + 8 * fq;
;                     const f32x4 a0 = *(const f32x4*)(xi + col) + acc[ai][bj][m][0], a1 = *(const f32x4*)(xi + col + 4) + acc[ai][bj][m][1];
;                     *(f32x4*)(xout + (size_t)row * DM + col) = a0; *(f32x4*)(xout + (size_t)row * DM + col + 4) = a1;
;                     u32x4 w; w.x = pk(a0[0], a0[1]); w.y = pk(a0[2], a0[3]); w.z = pk(a1[0], a1[1]); w.w = pk(a1[2], a1[3]);
;                     *(u32x4*)(xb + (size_t)row * DM + col) = w;
;                     sq += dot4(a0) + dot4(a1); }
;                 sq += __shfl_xor(sq, 16); sq += __shfl_xor(sq, 32);
;                 if (fq == 0) atomicAdd(ssout + row, sq);
;             }
	v_pk_add_f32 v[102:103], v[102:103], v[200:201]
	v_pk_add_f32 v[104:105], v[104:105], v[202:203]
	v_pk_add_f32 v[98:99], v[98:99], v[204:205]
	v_pk_add_f32 v[100:101], v[100:101], v[206:207]
	v_fmac_f32_e32 v229, v102, v102
	v_fmac_f32_e32 v230, v98, v98
	v_fmac_f32_e32 v229, v103, v103
	v_fmac_f32_e32 v230, v99, v99
	v_fmac_f32_e32 v229, v104, v104
	v_fmac_f32_e32 v230, v100, v100
	v_fmac_f32_e32 v229, v105, v105
	v_fmac_f32_e32 v230, v101, v101
	s_nop 1
	v_add_f32_dpp v229, v229, v229 quad_perm:[1,0,3,2] row_mask:0xf bank_mask:0xf
	v_add_f32_dpp v230, v230, v230 quad_perm:[1,0,3,2] row_mask:0xf bank_mask:0xf
	s_nop 0
	v_add_f32_dpp v229, v229, v229 quad_perm:[2,3,0,1] row_mask:0xf bank_mask:0xf
	v_add_f32_dpp v230, v230, v230 quad_perm:[2,3,0,1] row_mask:0xf bank_mask:0xf
	s_nop 0
	v_add_f32_dpp v229, v229, v229 row_half_mirror row_mask:0xf bank_mask:0xf
	v_add_f32_dpp v230, v230, v230 row_half_mirror row_mask:0xf bank_mask:0xf
	s_nop 0
	s_mov_b32 exec_lo, 0x1010101
	s_mov_b32 exec_hi, 0x1010101
	global_atomic_add_f32 v241, v229, s[10:11] offset:64
	global_atomic_add_f32 v241, v230, s[10:11] offset:96
	s_mov_b64 exec, -1
	v_add_u32_e32 v225, 0x80000, v245
	v_add_u32_e32 v226, 0x8000, v225
	global_load_dwordx4 v[192:195], v225, s[98:99]
	global_load_dwordx4 v[196:199], v226, s[98:99]
	global_load_dwordx4 v[200:203], v225, s[98:99] offset:512
	global_load_dwordx4 v[204:207], v226, s[98:99] offset:512
	s_waitcnt vmcnt(12)
	ds_write_b128 v246, v[94:97]
	ds_write_b128 v246, v[90:93] offset:16
	ds_read_b128 v[94:97], v224
	ds_read_b128 v[90:93], v224 offset:1152
	s_waitcnt lgkmcnt(0)
	v_pk_add_f32 v[94:95], v[94:95], v[208:209]
	v_pk_add_f32 v[96:97], v[96:97], v[210:211]
	v_pk_add_f32 v[90:91], v[90:91], v[212:213]
	v_pk_add_f32 v[92:93], v[92:93], v[214:215]
	v_mul_f32_e32 v229, v94, v94
	v_mul_f32_e32 v230, v90, v90
	v_fmac_f32_e32 v229, v95, v95
	v_fmac_f32_e32 v230, v91, v91
	v_fmac_f32_e32 v229, v96, v96
	v_fmac_f32_e32 v230, v92, v92
	v_fmac_f32_e32 v229, v97, v97
	v_fmac_f32_e32 v230, v93, v93
	ds_write_b128 v246, v[86:89]
	ds_write_b128 v246, v[82:85] offset:16
	ds_read_b128 v[86:89], v224
	ds_read_b128 v[82:85], v224 offset:1152
	s_waitcnt lgkmcnt(0)
	v_pk_add_f32 v[86:87], v[86:87], v[216:217]
	v_pk_add_f32 v[88:89], v[88:89], v[218:219]
	v_pk_add_f32 v[82:83], v[82:83], v[220:221]
	v_pk_add_f32 v[84:85], v[84:85], v[222:223]
	v_fmac_f32_e32 v229, v86, v86
	v_fmac_f32_e32 v230, v82, v82
	v_fmac_f32_e32 v229, v87, v87
	v_fmac_f32_e32 v230, v83, v83
	v_fmac_f32_e32 v229, v88, v88
	v_fmac_f32_e32 v230, v84, v84
	v_fmac_f32_e32 v229, v89, v89
	v_fmac_f32_e32 v230, v85, v85
	s_nop 1
	v_add_f32_dpp v229, v229, v229 quad_perm:[1,0,3,2] row_mask:0xf bank_mask:0xf
	v_add_f32_dpp v230, v230, v230 quad_perm:[1,0,3,2] row_mask:0xf bank_mask:0xf
	s_nop 0
	v_add_f32_dpp v229, v229, v229 quad_perm:[2,3,0,1] row_mask:0xf bank_mask:0xf
	v_add_f32_dpp v230, v230, v230 quad_perm:[2,3,0,1] row_mask:0xf bank_mask:0xf
	s_nop 0
	v_add_f32_dpp v229, v229, v229 row_half_mirror row_mask:0xf bank_mask:0xf
	v_add_f32_dpp v230, v230, v230 row_half_mirror row_mask:0xf bank_mask:0xf
	s_nop 0
	s_mov_b32 exec_lo, 0x1010101
	s_mov_b32 exec_hi, 0x1010101
	global_atomic_add_f32 v241, v229, s[10:11] offset:128
	global_atomic_add_f32 v241, v230, s[10:11] offset:160
	s_mov_b64 exec, -1
	v_add_u32_e32 v225, 0x90000, v245
	v_add_u32_e32 v226, 0x8000, v225
	global_load_dwordx4 v[208:211], v225, s[98:99]
	global_load_dwordx4 v[212:215], v226, s[98:99]
	global_load_dwordx4 v[216:219], v225, s[98:99] offset:512
	global_load_dwordx4 v[220:223], v226, s[98:99] offset:512
	s_waitcnt vmcnt(12)
	ds_write_b128 v246, v[78:81]
	ds_write_b128 v246, v[74:77] offset:16
	ds_read_b128 v[78:81], v224
	ds_read_b128 v[74:77], v224 offset:1152
	s_waitcnt lgkmcnt(0)
	v_pk_add_f32 v[78:79], v[78:79], v[176:177]
	v_pk_add_f32 v[80:81], v[80:81], v[178:179]
	v_pk_add_f32 v[74:75], v[74:75], v[180:181]
	v_pk_add_f32 v[76:77], v[76:77], v[182:183]
	v_mul_f32_e32 v229, v78, v78
	v_mul_f32_e32 v230, v74, v74
	v_fmac_f32_e32 v229, v79, v79
	v_fmac_f32_e32 v230, v75, v75
	v_fmac_f32_e32 v229, v80, v80
	v_fmac_f32_e32 v230, v76, v76
	v_fmac_f32_e32 v229, v81, v81
	v_fmac_f32_e32 v230, v77, v77
	ds_write_b128 v246, v[70:73]
	ds_write_b128 v246, v[66:69] offset:16
	ds_read_b128 v[70:73], v224
	ds_read_b128 v[66:69], v224 offset:1152
	s_waitcnt lgkmcnt(0)
	v_pk_add_f32 v[70:71], v[70:71], v[184:185]
	v_pk_add_f32 v[72:73], v[72:73], v[186:187]
	v_pk_add_f32 v[66:67], v[66:67], v[188:189]
	v_pk_add_f32 v[68:69], v[68:69], v[190:191]
	v_fmac_f32_e32 v229, v70, v70
	v_fmac_f32_e32 v230, v66, v66
	v_fmac_f32_e32 v229, v71, v71
	v_fmac_f32_e32 v230, v67, v67
	v_fmac_f32_e32 v229, v72, v72
	v_fmac_f32_e32 v230, v68, v68
	v_fmac_f32_e32 v229, v73, v73
	v_fmac_f32_e32 v230, v69, v69
	s_nop 1
	v_add_f32_dpp v229, v229, v229 quad_perm:[1,0,3,2] row_mask:0xf bank_mask:0xf
	v_add_f32_dpp v230, v230, v230 quad_perm:[1,0,3,2] row_mask:0xf bank_mask:0xf
	s_nop 0
	v_add_f32_dpp v229, v229, v229 quad_perm:[2,3,0,1] row_mask:0xf bank_mask:0xf
	v_add_f32_dpp v230, v230, v230 quad_perm:[2,3,0,1] row_mask:0xf bank_mask:0xf
	s_nop 0
	v_add_f32_dpp v229, v229, v229 row_half_mirror row_mask:0xf bank_mask:0xf
	v_add_f32_dpp v230, v230, v230 row_half_mirror row_mask:0xf bank_mask:0xf
	s_nop 0
	s_mov_b32 exec_lo, 0x1010101
	s_mov_b32 exec_hi, 0x1010101
	global_atomic_add_f32 v241, v229, s[10:11] offset:192
	global_atomic_add_f32 v241, v230, s[10:11] offset:224
	s_mov_b64 exec, -1
	v_add_u32_e32 v225, 0xa0000, v245
	v_add_u32_e32 v226, 0x8000, v225
	global_load_dwordx4 v[176:179], v225, s[98:99]
	global_load_dwordx4 v[180:183], v226, s[98:99]
	global_load_dwordx4 v[184:187], v225, s[98:99] offset:512
	global_load_dwordx4 v[188:191], v226, s[98:99] offset:512
	s_waitcnt vmcnt(12)
; __device__ __forceinline__ unsigned pk(float lo, float hi) { return pg8::cvt_pk_bf16(lo, hi); }
; __device__ __forceinline__ float dot4(f32x4 v) { return (v[0] * v[0] + v[1] * v[1]) + (v[2] * v[2] + v[3] * v[3]); }
;     __device__ __forceinline__ void operator()(const pg8::f32x4 (&acc)[2][2][4][2], const pg8::Unit& u, int wr, int wc, int fr, int fq) const {
;     ...
;             for (int m = 0; m < 4; ++m) {
;                 const int row = row0 + ai * 128 + m * 16;
;                 const float* xi = (row < MP) ? xin_p + (size_t)row * DM : xin_s + (size_t)(row - MP) * DM;
;                 float sq = 0.f;
; #pragma unroll
;                 for (int bj = 0; bj < 2; ++bj) { const int col = u.pn * 256 + bj * 128 + wc * 32 + 8 * fq;
;                     const f32x4 a0 = *(const f32x4*)(xi + col) + acc[ai][bj][m][0], a1 = *(const f32x4*)(xi + col + 4) + acc[ai][bj][m][1];
;                     *(f32x4*)(xout + (size_t)row * DM + col) = a0; *(f32x4*)(xout + (size_t)row * DM + col + 4) = a1;
;                     u32x4 w; w.x = pk(a0[0], a0[1]); w.y = pk(a0[2], a0[3]); w.z = pk(a1[0], a1[1]); w.w = pk(a1[2], a1[3]);
;                     *(u32x4*)(xb + (size_t)row * DM + col) = w;
;                     sq += dot4(a0) + dot4(a1); }
;                 sq += __shfl_xor(sq, 16); sq += __shfl_xor(sq, 32);
;                 if (fq == 0) atomicAdd(ssout + row, sq);
;             }
	ds_write_b128 v246, v[62:65]
	ds_write_b128 v246, v[58:61] offset:16
	ds_read_b128 v[62:65], v224
	ds_read_b128 v[58:61], v224 offset:1152
	s_waitcnt lgkmcnt(0)
	v_pk_add_f32 v[62:63], v[62:63], v[192:193]
	v_pk_add_f32 v[64:65], v[64:65], v[194:195]
	v_pk_add_f32 v[58:59], v[58:59], v[196:197]
	v_pk_add_f32 v[60:61], v[60:61], v[198:199]
	v_mul_f32_e32 v229, v62, v62
	v_mul_f32_e32 v230, v58, v58
	v_fmac_f32_e32 v229, v63, v63
	v_fmac_f32_e32 v230, v59, v59
	v_fmac_f32_e32 v229, v64, v64
	v_fmac_f32_e32 v230, v60, v60
	v_fmac_f32_e32 v229, v65, v65
	v_fmac_f32_e32 v230, v61, v61
	ds_write_b128 v246, v[54:57]
	ds_write_b128 v246, v[50:53] offset:16
	ds_read_b128 v[54:57], v224
	ds_read_b128 v[50:53], v224 offset:1152
	s_waitcnt lgkmcnt(0)
	v_pk_add_f32 v[54:55], v[54:55], v[200:201]
	v_pk_add_f32 v[56:57], v[56:57], v[202:203]
	v_pk_add_f32 v[50:51], v[50:51], v[204:205]
	v_pk_add_f32 v[52:53], v[52:53], v[206:207]
	v_fmac_f32_e32 v229, v54, v54
	v_fmac_f32_e32 v230, v50, v50
	v_fmac_f32_e32 v229, v55, v55
	v_fmac_f32_e32 v230, v51, v51
	v_fmac_f32_e32 v229, v56, v56
	v_fmac_f32_e32 v230, v52, v52
	v_fmac_f32_e32 v229, v57, v57
	v_fmac_f32_e32 v230, v53, v53
	s_nop 1
	v_add_f32_dpp v229, v229, v229 quad_perm:[1,0,3,2] row_mask:0xf bank_mask:0xf
	v_add_f32_dpp v230, v230, v230 quad_perm:[1,0,3,2] row_mask:0xf bank_mask:0xf
	s_nop 0
	v_add_f32_dpp v229, v229, v229 quad_perm:[2,3,0,1] row_mask:0xf bank_mask:0xf
	v_add_f32_dpp v230, v230, v230 quad_perm:[2,3,0,1] row_mask:0xf bank_mask:0xf
	s_nop 0
	v_add_f32_dpp v229, v229, v229 row_half_mirror row_mask:0xf bank_mask:0xf
	v_add_f32_dpp v230, v230, v230 row_half_mirror row_mask:0xf bank_mask:0xf
	s_nop 0
	s_mov_b32 exec_lo, 0x1010101
	s_mov_b32 exec_hi, 0x1010101
	global_atomic_add_f32 v241, v229, s[10:11] offset:512
	global_atomic_add_f32 v241, v230, s[10:11] offset:544
	s_mov_b64 exec, -1
	v_add_u32_e32 v225, 0xb0000, v245
	v_add_u32_e32 v226, 0x8000, v225
	global_load_dwordx4 v[192:195], v225, s[98:99]
	global_load_dwordx4 v[196:199], v226, s[98:99]
	global_load_dwordx4 v[200:203], v225, s[98:99] offset:512
	global_load_dwordx4 v[204:207], v226, s[98:99] offset:512
	s_waitcnt vmcnt(12)
	ds_write_b128 v246, v[46:49]
	ds_write_b128 v246, v[42:45] offset:16
	ds_read_b128 v[46:49], v224
	ds_read_b128 v[42:45], v224 offset:1152
	s_waitcnt lgkmcnt(0)
	v_pk_add_f32 v[46:47], v[46:47], v[208:209]
	v_pk_add_f32 v[48:49], v[48:49], v[210:211]
	v_pk_add_f32 v[42:43], v[42:43], v[212:213]
	v_pk_add_f32 v[44:45], v[44:45], v[214:215]
	v_mul_f32_e32 v229, v46, v46
	v_mul_f32_e32 v230, v42, v42
	v_fmac_f32_e32 v229, v47, v47
	v_fmac_f32_e32 v230, v43, v43
	v_fmac_f32_e32 v229, v48, v48
	v_fmac_f32_e32 v230, v44, v44
	v_fmac_f32_e32 v229, v49, v49
	v_fmac_f32_e32 v230, v45, v45
	ds_write_b128 v246, v[38:41]
	ds_write_b128 v246, v[34:37] offset:16
	ds_read_b128 v[38:41], v224
	ds_read_b128 v[34:37], v224 offset:1152
	s_waitcnt lgkmcnt(0)
	v_pk_add_f32 v[38:39], v[38:39], v[216:217]
	v_pk_add_f32 v[40:41], v[40:41], v[218:219]
	v_pk_add_f32 v[34:35], v[34:35], v[220:221]
	v_pk_add_f32 v[36:37], v[36:37], v[222:223]
	v_fmac_f32_e32 v229, v38, v38
	v_fmac_f32_e32 v230, v34, v34
	v_fmac_f32_e32 v229, v39, v39
	v_fmac_f32_e32 v230, v35, v35
	v_fmac_f32_e32 v229, v40, v40
	v_fmac_f32_e32 v230, v36, v36
	v_fmac_f32_e32 v229, v41, v41
	v_fmac_f32_e32 v230, v37, v37
	s_nop 1
	v_add_f32_dpp v229, v229, v229 quad_perm:[1,0,3,2] row_mask:0xf bank_mask:0xf
	v_add_f32_dpp v230, v230, v230 quad_perm:[1,0,3,2] row_mask:0xf bank_mask:0xf
	s_nop 0
	v_add_f32_dpp v229, v229, v229 quad_perm:[2,3,0,1] row_mask:0xf bank_mask:0xf
	v_add_f32_dpp v230, v230, v230 quad_perm:[2,3,0,1] row_mask:0xf bank_mask:0xf
	s_nop 0
	v_add_f32_dpp v229, v229, v229 row_half_mirror row_mask:0xf bank_mask:0xf
	v_add_f32_dpp v230, v230, v230 row_half_mirror row_mask:0xf bank_mask:0xf
	s_nop 0
	s_mov_b32 exec_lo, 0x1010101
	s_mov_b32 exec_hi, 0x1010101
	global_atomic_add_f32 v241, v229, s[10:11] offset:576
	global_atomic_add_f32 v241, v230, s[10:11] offset:608
	s_mov_b64 exec, -1
	s_waitcnt vmcnt(8)
	ds_write_b128 v246, v[30:33]
	ds_write_b128 v246, v[26:29] offset:16
	ds_read_b128 v[30:33], v224
	ds_read_b128 v[26:29], v224 offset:1152
	s_waitcnt lgkmcnt(0)
	v_pk_add_f32 v[30:31], v[30:31], v[176:177]
	v_pk_add_f32 v[32:33], v[32:33], v[178:179]
	v_pk_add_f32 v[26:27], v[26:27], v[180:181]
	v_pk_add_f32 v[28:29], v[28:29], v[182:183]
	v_mul_f32_e32 v229, v30, v30
	v_mul_f32_e32 v230, v26, v26
	v_fmac_f32_e32 v229, v31, v31
	v_fmac_f32_e32 v230, v27, v27
	v_fmac_f32_e32 v229, v32, v32
	v_fmac_f32_e32 v230, v28, v28
	v_fmac_f32_e32 v229, v33, v33
	v_fmac_f32_e32 v230, v29, v29
	ds_write_b128 v246, v[22:25]
	ds_write_b128 v246, v[18:21] offset:16
	ds_read_b128 v[22:25], v224
	ds_read_b128 v[18:21], v224 offset:1152
	s_waitcnt lgkmcnt(0)
	v_pk_add_f32 v[22:23], v[22:23], v[184:185]
	v_pk_add_f32 v[24:25], v[24:25], v[186:187]
	v_pk_add_f32 v[18:19], v[18:19], v[188:189]
	v_pk_add_f32 v[20:21], v[20:21], v[190:191]
	v_fmac_f32_e32 v229, v22, v22
	v_fmac_f32_e32 v230, v18, v18
	v_fmac_f32_e32 v229, v23, v23
	v_fmac_f32_e32 v230, v19, v19
	v_fmac_f32_e32 v229, v24, v24
	v_fmac_f32_e32 v230, v20, v20
	v_fmac_f32_e32 v229, v25, v25
	v_fmac_f32_e32 v230, v21, v21
	s_nop 1
	v_add_f32_dpp v229, v229, v229 quad_perm:[1,0,3,2] row_mask:0xf bank_mask:0xf
	v_add_f32_dpp v230, v230, v230 quad_perm:[1,0,3,2] row_mask:0xf bank_mask:0xf
	s_nop 0
	v_add_f32_dpp v229, v229, v229 quad_perm:[2,3,0,1] row_mask:0xf bank_mask:0xf
	v_add_f32_dpp v230, v230, v230 quad_perm:[2,3,0,1] row_mask:0xf bank_mask:0xf
	s_nop 0
	v_add_f32_dpp v229, v229, v229 row_half_mirror row_mask:0xf bank_mask:0xf
	v_add_f32_dpp v230, v230, v230 row_half_mirror row_mask:0xf bank_mask:0xf
	s_nop 0
	s_mov_b32 exec_lo, 0x1010101
	s_mov_b32 exec_hi, 0x1010101
	global_atomic_add_f32 v241, v229, s[10:11] offset:640
	global_atomic_add_f32 v241, v230, s[10:11] offset:672
	s_mov_b64 exec, -1
	s_waitcnt vmcnt(4)
; __device__ __forceinline__ float dot4(f32x4 v) { return (v[0] * v[0] + v[1] * v[1]) + (v[2] * v[2] + v[3] * v[3]); }
; __device__ __forceinline__ void p_final(const Args& a, int vcu, int G) {
;     ...
;     for (int j = 0; j < 4; ++j) gv[j] = ((const f32x4*)g)[lane + 64 * j];
;     for (int m0 = gw; m0 < MT; m0 += 3 * NGW) {
;         f32x4 v[3][4]; float rs[3];
; #pragma unroll
;         for (int q = 0; q < 3; ++q) { const int m = m0 + q * NGW; if (m < MT) { rs[q] = rsqrtf(ss[m] * (1.f / DM) + EPS);
; #pragma unroll
;             for (int j = 0; j < 4; ++j) v[q][j] = __builtin_nontemporal_load((const f32x4*)(XR + (size_t)m * DM) + lane + 64 * j); } }
;     __device__ __forceinline__ void operator()(const pg8::f32x4 (&acc)[2][2][4][2], const pg8::Unit& u, int wr, int wc, int fr, int fq) const {
;     ...
;                     sq += dot4(a0) + dot4(a1); }
;                 sq += __shfl_xor(sq, 16); sq += __shfl_xor(sq, 32);
;                 if (fq == 0) atomicAdd(ssout + row, sq);
	ds_write_b128 v246, v[14:17]
	ds_write_b128 v246, v[10:13] offset:16
	ds_read_b128 v[14:17], v224
	ds_read_b128 v[10:13], v224 offset:1152
	s_waitcnt lgkmcnt(0)
	v_pk_add_f32 v[14:15], v[14:15], v[192:193]
	v_pk_add_f32 v[16:17], v[16:17], v[194:195]
	v_pk_add_f32 v[10:11], v[10:11], v[196:197]
	v_pk_add_f32 v[12:13], v[12:13], v[198:199]
	v_mul_f32_e32 v229, v14, v14
	v_mul_f32_e32 v230, v10, v10
	v_fmac_f32_e32 v229, v15, v15
	v_fmac_f32_e32 v230, v11, v11
	v_fmac_f32_e32 v229, v16, v16
	v_fmac_f32_e32 v230, v12, v12
	v_fmac_f32_e32 v229, v17, v17
	v_fmac_f32_e32 v230, v13, v13
	ds_write_b128 v246, v[6:9]
	ds_write_b128 v246, v[2:5] offset:16
	ds_read_b128 v[6:9], v224
	ds_read_b128 v[2:5], v224 offset:1152
	s_waitcnt lgkmcnt(0)
	v_pk_add_f32 v[6:7], v[6:7], v[200:201]
	v_pk_add_f32 v[8:9], v[8:9], v[202:203]
	v_pk_add_f32 v[2:3], v[2:3], v[204:205]
	v_pk_add_f32 v[4:5], v[4:5], v[206:207]
	v_fmac_f32_e32 v229, v6, v6
	v_fmac_f32_e32 v230, v2, v2
	v_fmac_f32_e32 v229, v7, v7
	v_fmac_f32_e32 v230, v3, v3
	v_fmac_f32_e32 v229, v8, v8
	v_fmac_f32_e32 v230, v4, v4
	v_fmac_f32_e32 v229, v9, v9
	v_fmac_f32_e32 v230, v5, v5
	s_nop 1
	v_add_f32_dpp v229, v229, v229 quad_perm:[1,0,3,2] row_mask:0xf bank_mask:0xf
	v_add_f32_dpp v230, v230, v230 quad_perm:[1,0,3,2] row_mask:0xf bank_mask:0xf
	s_nop 0
	v_add_f32_dpp v229, v229, v229 quad_perm:[2,3,0,1] row_mask:0xf bank_mask:0xf
	v_add_f32_dpp v230, v230, v230 quad_perm:[2,3,0,1] row_mask:0xf bank_mask:0xf
	s_nop 0
	v_add_f32_dpp v229, v229, v229 row_half_mirror row_mask:0xf bank_mask:0xf
	v_add_f32_dpp v230, v230, v230 row_half_mirror row_mask:0xf bank_mask:0xf
	s_nop 0
	s_mov_b32 exec_lo, 0x1010101
	s_mov_b32 exec_hi, 0x1010101
	global_atomic_add_f32 v241, v229, s[10:11] offset:704
	global_atomic_add_f32 v241, v230, s[10:11] offset:736
	s_mov_b64 exec, -1
	s_waitcnt vmcnt(0)
	s_barrier
	v_readlane_b32 s98, v252, 4
	v_readlane_b32 s99, v252, 5
	v_readlane_b32 s100, v252, 6
	v_readlane_b32 s101, v252, 7
	v_cmp_eq_u32_e32 vcc, 0, v0
	s_nop 1
	s_mov_b64 exec, vcc
	s_cbranch_execz .Lfin_join
	v_mov_b32_e32 v234, 1
	global_atomic_add v233, v234, s[28:29]
	s_waitcnt vmcnt(0)
	v_mov_b32_e32 v236, 0
.Lfin_spin:
	global_load_dword v235, v233, s[28:29] sc1
	s_waitcnt vmcnt(0)
	v_cmp_gt_u32_e32 vcc, 4, v235
	s_cbranch_vccz .Lfin_join
	s_sleep 1
	v_add_u32_e32 v236, 1, v236
	v_cmp_gt_u32_e32 vcc, 0x8000, v236
	s_cbranch_vccnz .Lfin_spin
.Lfin_join:
	s_mov_b64 exec, -1
	s_barrier
	global_load_dwordx4 v[208:211], v240, s[98:99]
	global_load_dwordx4 v[212:215], v240, s[98:99] offset:512
	global_load_dword v176, v241, s[10:11] sc1
	global_load_dword v192, v241, s[10:11] offset:32 sc1
	global_load_dword v178, v241, s[10:11] offset:64 sc1
	global_load_dword v194, v241, s[10:11] offset:96 sc1
	global_load_dword v180, v241, s[10:11] offset:128 sc1
	global_load_dword v196, v241, s[10:11] offset:160 sc1
	global_load_dword v182, v241, s[10:11] offset:192 sc1
	global_load_dword v198, v241, s[10:11] offset:224 sc1
	global_load_dword v184, v241, s[10:11] offset:512 sc1
	global_load_dword v200, v241, s[10:11] offset:544 sc1
	global_load_dword v186, v241, s[10:11] offset:576 sc1
	global_load_dword v202, v241, s[10:11] offset:608 sc1
	global_load_dword v188, v241, s[10:11] offset:640 sc1
	global_load_dword v204, v241, s[10:11] offset:672 sc1
	global_load_dword v190, v241, s[10:11] offset:704 sc1
	global_load_dword v206, v241, s[10:11] offset:736 sc1
	v_mov_b32_e32 v237, 0x358637bd
	s_waitcnt vmcnt(0)
	v_fmamk_f32 v176, v176, 0x3a800000, v237
	v_fmamk_f32 v178, v178, 0x3a800000, v237
	v_fmamk_f32 v180, v180, 0x3a800000, v237
	v_fmamk_f32 v182, v182, 0x3a800000, v237
	v_fmamk_f32 v184, v184, 0x3a800000, v237
	v_fmamk_f32 v186, v186, 0x3a800000, v237
	v_fmamk_f32 v188, v188, 0x3a800000, v237
	v_fmamk_f32 v190, v190, 0x3a800000, v237
	v_fmamk_f32 v192, v192, 0x3a800000, v237
	v_fmamk_f32 v194, v194, 0x3a800000, v237
	v_fmamk_f32 v196, v196, 0x3a800000, v237
	v_fmamk_f32 v198, v198, 0x3a800000, v237
	v_fmamk_f32 v200, v200, 0x3a800000, v237
	v_fmamk_f32 v202, v202, 0x3a800000, v237
	v_fmamk_f32 v204, v204, 0x3a800000, v237
	v_fmamk_f32 v206, v206, 0x3a800000, v237
	v_mul_f32_e32 v231, 0x4b800000, v176
	v_cmp_gt_f32_e32 vcc, 0x800000, v176
	s_nop 1
	v_cndmask_b32_e32 v176, v176, v231, vcc
	v_rsq_f32_e32 v176, v176
	s_nop 0
	v_mul_f32_e32 v231, 0x45800000, v176
	v_cndmask_b32_e32 v176, v176, v231, vcc
	v_mul_f32_e32 v231, 0x4b800000, v178
	v_cmp_gt_f32_e32 vcc, 0x800000, v178
	s_nop 1
	v_cndmask_b32_e32 v178, v178, v231, vcc
	v_rsq_f32_e32 v178, v178
	s_nop 0
	v_mul_f32_e32 v231, 0x45800000, v178
	v_cndmask_b32_e32 v178, v178, v231, vcc
	v_mul_f32_e32 v231, 0x4b800000, v180
	v_cmp_gt_f32_e32 vcc, 0x800000, v180
	s_nop 1
	v_cndmask_b32_e32 v180, v180, v231, vcc
	v_rsq_f32_e32 v180, v180
	s_nop 0
	v_mul_f32_e32 v231, 0x45800000, v180
	v_cndmask_b32_e32 v180, v180, v231, vcc
	v_mul_f32_e32 v231, 0x4b800000, v182
	v_cmp_gt_f32_e32 vcc, 0x800000, v182
	s_nop 1
	v_cndmask_b32_e32 v182, v182, v231, vcc
	v_rsq_f32_e32 v182, v182
	s_nop 0
	v_mul_f32_e32 v231, 0x45800000, v182
	v_cndmask_b32_e32 v182, v182, v231, vcc
	v_mul_f32_e32 v231, 0x4b800000, v184
	v_cmp_gt_f32_e32 vcc, 0x800000, v184
	s_nop 1
	v_cndmask_b32_e32 v184, v184, v231, vcc
	v_rsq_f32_e32 v184, v184
	s_nop 0
	v_mul_f32_e32 v231, 0x45800000, v184
	v_cndmask_b32_e32 v184, v184, v231, vcc
	v_mul_f32_e32 v231, 0x4b800000, v186
	v_cmp_gt_f32_e32 vcc, 0x800000, v186
	s_nop 1
	v_cndmask_b32_e32 v186, v186, v231, vcc
	v_rsq_f32_e32 v186, v186
	s_nop 0
	v_mul_f32_e32 v231, 0x45800000, v186
	v_cndmask_b32_e32 v186, v186, v231, vcc
	v_mul_f32_e32 v231, 0x4b800000, v188
; __device__ __forceinline__ void p_final(const Args& a, int vcu, int G) {
;     ...
;         for (int q = 0; q < 3; ++q) { const int m = m0 + q * NGW; if (m < MT) { rs[q] = rsqrtf(ss[m] * (1.f / DM) + EPS);
; #pragma unroll
;             for (int j = 0; j < 4; ++j) v[q][j] = __builtin_nontemporal_load((const f32x4*)(XR + (size_t)m * DM) + lane + 64 * j); } }
; #pragma unroll
;         for (int q = 0; q < 3; ++q) { const int m = m0 + q * NGW; if (m < MT) {
; #pragma unroll
;             for (int j = 0; j < 4; ++j) __builtin_nontemporal_store(v[q][j] * rs[q] * gv[j], (f32x4*)(a.out + O_Y + (size_t)m * DM) + lane + 64 * j); } }
	v_cmp_gt_f32_e32 vcc, 0x800000, v188
	s_nop 1
	v_cndmask_b32_e32 v188, v188, v231, vcc
	v_rsq_f32_e32 v188, v188
	s_nop 0
	v_mul_f32_e32 v231, 0x45800000, v188
	v_cndmask_b32_e32 v188, v188, v231, vcc
	v_mul_f32_e32 v231, 0x4b800000, v190
	v_cmp_gt_f32_e32 vcc, 0x800000, v190
	s_nop 1
	v_cndmask_b32_e32 v190, v190, v231, vcc
	v_rsq_f32_e32 v190, v190
	s_nop 0
	v_mul_f32_e32 v231, 0x45800000, v190
	v_cndmask_b32_e32 v190, v190, v231, vcc
	v_mul_f32_e32 v231, 0x4b800000, v192
	v_cmp_gt_f32_e32 vcc, 0x800000, v192
	s_nop 1
	v_cndmask_b32_e32 v192, v192, v231, vcc
	v_rsq_f32_e32 v192, v192
	s_nop 0
	v_mul_f32_e32 v231, 0x45800000, v192
	v_cndmask_b32_e32 v192, v192, v231, vcc
	v_mul_f32_e32 v231, 0x4b800000, v194
	v_cmp_gt_f32_e32 vcc, 0x800000, v194
	s_nop 1
	v_cndmask_b32_e32 v194, v194, v231, vcc
	v_rsq_f32_e32 v194, v194
	s_nop 0
	v_mul_f32_e32 v231, 0x45800000, v194
	v_cndmask_b32_e32 v194, v194, v231, vcc
	v_mul_f32_e32 v231, 0x4b800000, v196
	v_cmp_gt_f32_e32 vcc, 0x800000, v196
	s_nop 1
	v_cndmask_b32_e32 v196, v196, v231, vcc
	v_rsq_f32_e32 v196, v196
	s_nop 0
	v_mul_f32_e32 v231, 0x45800000, v196
	v_cndmask_b32_e32 v196, v196, v231, vcc
	v_mul_f32_e32 v231, 0x4b800000, v198
	v_cmp_gt_f32_e32 vcc, 0x800000, v198
	s_nop 1
	v_cndmask_b32_e32 v198, v198, v231, vcc
	v_rsq_f32_e32 v198, v198
	s_nop 0
	v_mul_f32_e32 v231, 0x45800000, v198
	v_cndmask_b32_e32 v198, v198, v231, vcc
	v_mul_f32_e32 v231, 0x4b800000, v200
	v_cmp_gt_f32_e32 vcc, 0x800000, v200
	s_nop 1
	v_cndmask_b32_e32 v200, v200, v231, vcc
	v_rsq_f32_e32 v200, v200
	s_nop 0
	v_mul_f32_e32 v231, 0x45800000, v200
	v_cndmask_b32_e32 v200, v200, v231, vcc
	v_mul_f32_e32 v231, 0x4b800000, v202
	v_cmp_gt_f32_e32 vcc, 0x800000, v202
	s_nop 1
	v_cndmask_b32_e32 v202, v202, v231, vcc
	v_rsq_f32_e32 v202, v202
	s_nop 0
	v_mul_f32_e32 v231, 0x45800000, v202
	v_cndmask_b32_e32 v202, v202, v231, vcc
	v_mul_f32_e32 v231, 0x4b800000, v204
	v_cmp_gt_f32_e32 vcc, 0x800000, v204
	s_nop 1
	v_cndmask_b32_e32 v204, v204, v231, vcc
	v_rsq_f32_e32 v204, v204
	s_nop 0
	v_mul_f32_e32 v231, 0x45800000, v204
	v_cndmask_b32_e32 v204, v204, v231, vcc
	v_mul_f32_e32 v231, 0x4b800000, v206
	v_cmp_gt_f32_e32 vcc, 0x800000, v206
	s_nop 1
	v_cndmask_b32_e32 v206, v206, v231, vcc
	v_rsq_f32_e32 v206, v206
	s_nop 0
	v_mul_f32_e32 v231, 0x45800000, v206
	v_cndmask_b32_e32 v206, v206, v231, vcc
	v_add_u32_e32 v228, 0x8000, v242
	v_pk_mul_f32 v[126:127], v[126:127], v[176:177] op_sel_hi:[1,0]
	v_pk_mul_f32 v[128:129], v[128:129], v[176:177] op_sel_hi:[1,0]
	v_pk_mul_f32 v[126:127], v[126:127], v[208:209]
	v_pk_mul_f32 v[128:129], v[128:129], v[210:211]
	v_pk_mul_f32 v[122:123], v[122:123], v[192:193] op_sel_hi:[1,0]
	v_pk_mul_f32 v[124:125], v[124:125], v[192:193] op_sel_hi:[1,0]
	v_pk_mul_f32 v[122:123], v[122:123], v[208:209]
	v_pk_mul_f32 v[124:125], v[124:125], v[210:211]
	global_store_dwordx4 v242, v[126:129], s[100:101] nt
	global_store_dwordx4 v228, v[122:125], s[100:101] nt
	v_pk_mul_f32 v[118:119], v[118:119], v[176:177] op_sel_hi:[1,0]
	v_pk_mul_f32 v[120:121], v[120:121], v[176:177] op_sel_hi:[1,0]
	v_pk_mul_f32 v[118:119], v[118:119], v[212:213]
	v_pk_mul_f32 v[120:121], v[120:121], v[214:215]
	v_pk_mul_f32 v[114:115], v[114:115], v[192:193] op_sel_hi:[1,0]
	v_pk_mul_f32 v[116:117], v[116:117], v[192:193] op_sel_hi:[1,0]
	v_pk_mul_f32 v[114:115], v[114:115], v[212:213]
	v_pk_mul_f32 v[116:117], v[116:117], v[214:215]
	global_store_dwordx4 v242, v[118:121], s[100:101] offset:512 nt
	global_store_dwordx4 v228, v[114:117], s[100:101] offset:512 nt
	v_add_u32_e32 v227, 0x10000, v242
	v_add_u32_e32 v228, 0x8000, v227
	v_pk_mul_f32 v[110:111], v[110:111], v[178:179] op_sel_hi:[1,0]
	v_pk_mul_f32 v[112:113], v[112:113], v[178:179] op_sel_hi:[1,0]
	v_pk_mul_f32 v[110:111], v[110:111], v[208:209]
	v_pk_mul_f32 v[112:113], v[112:113], v[210:211]
	v_pk_mul_f32 v[106:107], v[106:107], v[194:195] op_sel_hi:[1,0]
	v_pk_mul_f32 v[108:109], v[108:109], v[194:195] op_sel_hi:[1,0]
	v_pk_mul_f32 v[106:107], v[106:107], v[208:209]
	v_pk_mul_f32 v[108:109], v[108:109], v[210:211]
	global_store_dwordx4 v227, v[110:113], s[100:101] nt
	global_store_dwordx4 v228, v[106:109], s[100:101] nt
	v_pk_mul_f32 v[102:103], v[102:103], v[178:179] op_sel_hi:[1,0]
	v_pk_mul_f32 v[104:105], v[104:105], v[178:179] op_sel_hi:[1,0]
	v_pk_mul_f32 v[102:103], v[102:103], v[212:213]
	v_pk_mul_f32 v[104:105], v[104:105], v[214:215]
	v_pk_mul_f32 v[98:99], v[98:99], v[194:195] op_sel_hi:[1,0]
	v_pk_mul_f32 v[100:101], v[100:101], v[194:195] op_sel_hi:[1,0]
	v_pk_mul_f32 v[98:99], v[98:99], v[212:213]
	v_pk_mul_f32 v[100:101], v[100:101], v[214:215]
	global_store_dwordx4 v227, v[102:105], s[100:101] offset:512 nt
	global_store_dwordx4 v228, v[98:101], s[100:101] offset:512 nt
	v_add_u32_e32 v227, 0x20000, v242
	v_add_u32_e32 v228, 0x8000, v227
	v_pk_mul_f32 v[94:95], v[94:95], v[180:181] op_sel_hi:[1,0]
	v_pk_mul_f32 v[96:97], v[96:97], v[180:181] op_sel_hi:[1,0]
	v_pk_mul_f32 v[94:95], v[94:95], v[208:209]
	v_pk_mul_f32 v[96:97], v[96:97], v[210:211]
	v_pk_mul_f32 v[90:91], v[90:91], v[196:197] op_sel_hi:[1,0]
	v_pk_mul_f32 v[92:93], v[92:93], v[196:197] op_sel_hi:[1,0]
	v_pk_mul_f32 v[90:91], v[90:91], v[208:209]
	v_pk_mul_f32 v[92:93], v[92:93], v[210:211]
	global_store_dwordx4 v227, v[94:97], s[100:101] nt
	global_store_dwordx4 v228, v[90:93], s[100:101] nt
	v_pk_mul_f32 v[86:87], v[86:87], v[180:181] op_sel_hi:[1,0]
	v_pk_mul_f32 v[88:89], v[88:89], v[180:181] op_sel_hi:[1,0]
	v_pk_mul_f32 v[86:87], v[86:87], v[212:213]
	v_pk_mul_f32 v[88:89], v[88:89], v[214:215]
	v_pk_mul_f32 v[82:83], v[82:83], v[196:197] op_sel_hi:[1,0]
; __device__ __forceinline__ void p_final(const Args& a, int vcu, int G) {
;     ...
;         for (int q = 0; q < 3; ++q) { const int m = m0 + q * NGW; if (m < MT) {
; #pragma unroll
;             for (int j = 0; j < 4; ++j) __builtin_nontemporal_store(v[q][j] * rs[q] * gv[j], (f32x4*)(a.out + O_Y + (size_t)m * DM) + lane + 64 * j); } }
	v_pk_mul_f32 v[84:85], v[84:85], v[196:197] op_sel_hi:[1,0]
	v_pk_mul_f32 v[82:83], v[82:83], v[212:213]
	v_pk_mul_f32 v[84:85], v[84:85], v[214:215]
	global_store_dwordx4 v227, v[86:89], s[100:101] offset:512 nt
	global_store_dwordx4 v228, v[82:85], s[100:101] offset:512 nt
	v_add_u32_e32 v227, 0x30000, v242
	v_add_u32_e32 v228, 0x8000, v227
	v_pk_mul_f32 v[78:79], v[78:79], v[182:183] op_sel_hi:[1,0]
	v_pk_mul_f32 v[80:81], v[80:81], v[182:183] op_sel_hi:[1,0]
	v_pk_mul_f32 v[78:79], v[78:79], v[208:209]
	v_pk_mul_f32 v[80:81], v[80:81], v[210:211]
	v_pk_mul_f32 v[74:75], v[74:75], v[198:199] op_sel_hi:[1,0]
	v_pk_mul_f32 v[76:77], v[76:77], v[198:199] op_sel_hi:[1,0]
	v_pk_mul_f32 v[74:75], v[74:75], v[208:209]
	v_pk_mul_f32 v[76:77], v[76:77], v[210:211]
	global_store_dwordx4 v227, v[78:81], s[100:101] nt
	global_store_dwordx4 v228, v[74:77], s[100:101] nt
	v_pk_mul_f32 v[70:71], v[70:71], v[182:183] op_sel_hi:[1,0]
	v_pk_mul_f32 v[72:73], v[72:73], v[182:183] op_sel_hi:[1,0]
	v_pk_mul_f32 v[70:71], v[70:71], v[212:213]
	v_pk_mul_f32 v[72:73], v[72:73], v[214:215]
	v_pk_mul_f32 v[66:67], v[66:67], v[198:199] op_sel_hi:[1,0]
	v_pk_mul_f32 v[68:69], v[68:69], v[198:199] op_sel_hi:[1,0]
	v_pk_mul_f32 v[66:67], v[66:67], v[212:213]
	v_pk_mul_f32 v[68:69], v[68:69], v[214:215]
	global_store_dwordx4 v227, v[70:73], s[100:101] offset:512 nt
	global_store_dwordx4 v228, v[66:69], s[100:101] offset:512 nt
	v_add_u32_e32 v227, 0x80000, v242
	v_add_u32_e32 v228, 0x8000, v227
	v_pk_mul_f32 v[62:63], v[62:63], v[184:185] op_sel_hi:[1,0]
	v_pk_mul_f32 v[64:65], v[64:65], v[184:185] op_sel_hi:[1,0]
	v_pk_mul_f32 v[62:63], v[62:63], v[208:209]
	v_pk_mul_f32 v[64:65], v[64:65], v[210:211]
	v_pk_mul_f32 v[58:59], v[58:59], v[200:201] op_sel_hi:[1,0]
	v_pk_mul_f32 v[60:61], v[60:61], v[200:201] op_sel_hi:[1,0]
	v_pk_mul_f32 v[58:59], v[58:59], v[208:209]
	v_pk_mul_f32 v[60:61], v[60:61], v[210:211]
	global_store_dwordx4 v227, v[62:65], s[100:101] nt
	global_store_dwordx4 v228, v[58:61], s[100:101] nt
	v_pk_mul_f32 v[54:55], v[54:55], v[184:185] op_sel_hi:[1,0]
	v_pk_mul_f32 v[56:57], v[56:57], v[184:185] op_sel_hi:[1,0]
	v_pk_mul_f32 v[54:55], v[54:55], v[212:213]
	v_pk_mul_f32 v[56:57], v[56:57], v[214:215]
	v_pk_mul_f32 v[50:51], v[50:51], v[200:201] op_sel_hi:[1,0]
	v_pk_mul_f32 v[52:53], v[52:53], v[200:201] op_sel_hi:[1,0]
	v_pk_mul_f32 v[50:51], v[50:51], v[212:213]
	v_pk_mul_f32 v[52:53], v[52:53], v[214:215]
	global_store_dwordx4 v227, v[54:57], s[100:101] offset:512 nt
	global_store_dwordx4 v228, v[50:53], s[100:101] offset:512 nt
	v_add_u32_e32 v227, 0x90000, v242
	v_add_u32_e32 v228, 0x8000, v227
	v_pk_mul_f32 v[46:47], v[46:47], v[186:187] op_sel_hi:[1,0]
	v_pk_mul_f32 v[48:49], v[48:49], v[186:187] op_sel_hi:[1,0]
	v_pk_mul_f32 v[46:47], v[46:47], v[208:209]
	v_pk_mul_f32 v[48:49], v[48:49], v[210:211]
	v_pk_mul_f32 v[42:43], v[42:43], v[202:203] op_sel_hi:[1,0]
	v_pk_mul_f32 v[44:45], v[44:45], v[202:203] op_sel_hi:[1,0]
	v_pk_mul_f32 v[42:43], v[42:43], v[208:209]
	v_pk_mul_f32 v[44:45], v[44:45], v[210:211]
	global_store_dwordx4 v227, v[46:49], s[100:101] nt
	global_store_dwordx4 v228, v[42:45], s[100:101] nt
	v_pk_mul_f32 v[38:39], v[38:39], v[186:187] op_sel_hi:[1,0]
	v_pk_mul_f32 v[40:41], v[40:41], v[186:187] op_sel_hi:[1,0]
	v_pk_mul_f32 v[38:39], v[38:39], v[212:213]
	v_pk_mul_f32 v[40:41], v[40:41], v[214:215]
	v_pk_mul_f32 v[34:35], v[34:35], v[202:203] op_sel_hi:[1,0]
	v_pk_mul_f32 v[36:37], v[36:37], v[202:203] op_sel_hi:[1,0]
	v_pk_mul_f32 v[34:35], v[34:35], v[212:213]
	v_pk_mul_f32 v[36:37], v[36:37], v[214:215]
	global_store_dwordx4 v227, v[38:41], s[100:101] offset:512 nt
	global_store_dwordx4 v228, v[34:37], s[100:101] offset:512 nt
	v_add_u32_e32 v227, 0xa0000, v242
	v_add_u32_e32 v228, 0x8000, v227
	v_pk_mul_f32 v[30:31], v[30:31], v[188:189] op_sel_hi:[1,0]
	v_pk_mul_f32 v[32:33], v[32:33], v[188:189] op_sel_hi:[1,0]
	v_pk_mul_f32 v[30:31], v[30:31], v[208:209]
	v_pk_mul_f32 v[32:33], v[32:33], v[210:211]
	v_pk_mul_f32 v[26:27], v[26:27], v[204:205] op_sel_hi:[1,0]
	v_pk_mul_f32 v[28:29], v[28:29], v[204:205] op_sel_hi:[1,0]
	v_pk_mul_f32 v[26:27], v[26:27], v[208:209]
	v_pk_mul_f32 v[28:29], v[28:29], v[210:211]
	global_store_dwordx4 v227, v[30:33], s[100:101] nt
	global_store_dwordx4 v228, v[26:29], s[100:101] nt
	v_pk_mul_f32 v[22:23], v[22:23], v[188:189] op_sel_hi:[1,0]
	v_pk_mul_f32 v[24:25], v[24:25], v[188:189] op_sel_hi:[1,0]
	v_pk_mul_f32 v[22:23], v[22:23], v[212:213]
	v_pk_mul_f32 v[24:25], v[24:25], v[214:215]
	v_pk_mul_f32 v[18:19], v[18:19], v[204:205] op_sel_hi:[1,0]
	v_pk_mul_f32 v[20:21], v[20:21], v[204:205] op_sel_hi:[1,0]
	v_pk_mul_f32 v[18:19], v[18:19], v[212:213]
	v_pk_mul_f32 v[20:21], v[20:21], v[214:215]
	global_store_dwordx4 v227, v[22:25], s[100:101] offset:512 nt
	global_store_dwordx4 v228, v[18:21], s[100:101] offset:512 nt
	v_add_u32_e32 v227, 0xb0000, v242
	v_add_u32_e32 v228, 0x8000, v227
	v_pk_mul_f32 v[14:15], v[14:15], v[190:191] op_sel_hi:[1,0]
	v_pk_mul_f32 v[16:17], v[16:17], v[190:191] op_sel_hi:[1,0]
	v_pk_mul_f32 v[14:15], v[14:15], v[208:209]
	v_pk_mul_f32 v[16:17], v[16:17], v[210:211]
	v_pk_mul_f32 v[10:11], v[10:11], v[206:207] op_sel_hi:[1,0]
	v_pk_mul_f32 v[12:13], v[12:13], v[206:207] op_sel_hi:[1,0]
	v_pk_mul_f32 v[10:11], v[10:11], v[208:209]
	v_pk_mul_f32 v[12:13], v[12:13], v[210:211]
	global_store_dwordx4 v227, v[14:17], s[100:101] nt
	global_store_dwordx4 v228, v[10:13], s[100:101] nt
	v_pk_mul_f32 v[6:7], v[6:7], v[190:191] op_sel_hi:[1,0]
	v_pk_mul_f32 v[8:9], v[8:9], v[190:191] op_sel_hi:[1,0]
	v_pk_mul_f32 v[6:7], v[6:7], v[212:213]
	v_pk_mul_f32 v[8:9], v[8:9], v[214:215]
	v_pk_mul_f32 v[2:3], v[2:3], v[206:207] op_sel_hi:[1,0]
	v_pk_mul_f32 v[4:5], v[4:5], v[206:207] op_sel_hi:[1,0]
	v_pk_mul_f32 v[2:3], v[2:3], v[212:213]
	v_pk_mul_f32 v[4:5], v[4:5], v[214:215]
	global_store_dwordx4 v227, v[6:9], s[100:101] offset:512 nt
	global_store_dwordx4 v228, v[2:5], s[100:101] offset:512 nt
	s_and_b64 vcc, exec, s[4:5]
	s_mov_b64 s[4:5], -1
	s_cbranch_vccnz .LBB0_2074
	s_andn2_b64 vcc, exec, s[18:19]
	s_cbranch_vccnz .LBB0_2073
	s_barrier
	s_branch .LBB0_2073
